# RG-LRU scan: multiply-by-zero FMAs removed
# baseline (speedup 1.0000x reference)
.LBB0_209:
	v_mov_b32_e32 v0, v52
	v_readlane_b32 s0, v255, 8
	v_and_b32_e32 v101, 15, v0
	v_lshlrev_b32_e32 v104, 3, v0
	v_bfe_u32 v88, v0, 4, 2
	v_lshrrev_b32_e32 v1, 2, v0
	v_and_b32_e32 v54, 56, v104
	v_ashrrev_i32_e32 v48, 3, v0
	v_add_u32_e32 v0, 0x200, v0
	v_or_b32_e32 v90, s34, v101
	v_or_b32_e32 v2, s0, v54
	v_ashrrev_i32_e32 v57, 3, v0
	v_mul_lo_u32 v0, v90, s60
	v_readlane_b32 s0, v255, 9
	s_and_b32 s41, s40, 1
	v_lshlrev_b32_e32 v91, 4, v88
	v_add_lshl_u32 v56, v0, s0, 1
	s_add_u32 s0, s39, s54
	v_or_b32_e32 v50, 0x400, v2
	v_or_b32_e32 v59, 0x500, v2
	v_or_b32_e32 v2, v56, v91
	s_addc_u32 s1, s78, s55
	v_and_or_b32 v55, v1, 14, s34
	v_lshl_add_u64 v[0:1], s[0:1], 0, v[2:3]
	v_add_co_u32_e32 v0, vcc, s63, v0
	s_lshl_b32 s8, s41, 7
	s_nop 0
	v_addc_co_u32_e32 v1, vcc, 0, v1, vcc
	global_load_dwordx4 v[44:47], v[0:1], off
	global_load_dwordx4 v[40:43], v[0:1], off offset:64
	v_lshl_add_u32 v0, v54, 1, 0
	v_add_u32_e32 v1, s8, v48
	v_mul_lo_u32 v51, v48, s60
	v_mad_u64_u32 v[48:49], s[6:7], v1, s61, v[0:1]
	v_add_u32_e32 v1, s8, v57
	v_mad_u64_u32 v[0:1], s[6:7], v1, s61, v[0:1]
	v_lshlrev_b32_e32 v1, 2, v54
	s_cmp_eq_u32 s54, 0
	v_mul_lo_u32 v58, v57, s60
	v_add_u32_e32 v57, 0, v1
	s_cselect_b64 s[6:7], -1, 0
	s_add_i32 s10, 0, 0x1f000
	v_cmp_gt_i32_e32 vcc, 3, v55
	ds_write_b128 v48, v[4:7]
	ds_write_b128 v0, v[8:11]
	v_add_lshl_u32 v70, v50, v58, 1
	v_add_lshl_u32 v72, v59, v58, 1
	ds_write_b128 v48, v[12:15] offset:36864
	ds_write_b128 v0, v[16:19] offset:36864
	v_add_u32_e32 v0, 0x1f400, v57
	v_add_u32_e32 v58, s10, v1
	s_and_b64 s[8:9], s[6:7], vcc
	v_cmp_gt_i32_e32 vcc, 2, v55
	ds_read_b128 v[4:7], v0
	ds_read_b128 v[8:11], v0 offset:16
	s_waitcnt vmcnt(8)
	v_cndmask_b32_e64 v64, v31, 0, s[8:9]
	v_cndmask_b32_e64 v65, v30, 0, s[8:9]
	v_cndmask_b32_e64 v66, v29, 0, s[8:9]
	v_cndmask_b32_e64 v63, v28, 0, s[8:9]
	ds_read_b128 v[12:15], v58
	ds_read_b128 v[16:19], v58 offset:16
	s_and_b64 s[8:9], s[6:7], vcc
	v_cmp_gt_i32_e32 vcc, 1, v55
	s_waitcnt vmcnt(7)
	v_cndmask_b32_e64 v67, v27, 0, s[8:9]
	v_cndmask_b32_e64 v68, v26, 0, s[8:9]
	v_cndmask_b32_e64 v69, v25, 0, s[8:9]
	v_cndmask_b32_e64 v71, v24, 0, s[8:9]
	ds_read_b128 v[24:27], v58 offset:256
	ds_read_b128 v[28:31], v58 offset:272
	s_and_b64 s[8:9], s[6:7], vcc
	v_add_lshl_u32 v2, v50, v51, 1
	v_add_lshl_u32 v0, v59, v51, 1
	s_waitcnt vmcnt(6)
	v_cndmask_b32_e64 v73, v39, 0, s[8:9]
	v_cndmask_b32_e64 v89, v38, 0, s[8:9]
	v_cndmask_b32_e64 v83, v37, 0, s[8:9]
	v_cndmask_b32_e64 v77, v36, 0, s[8:9]
	ds_read_b128 v[36:39], v58 offset:512
	ds_read_b128 v[48:51], v58 offset:528
	v_lshlrev_b32_e32 v62, 16, v63
	v_and_b32_e32 v63, 0xffff0000, v63
	s_waitcnt lgkmcnt(5)
	v_pk_fma_f32 v[62:63], v[12:13], v[62:63], v[4:5]
	v_lshlrev_b32_e32 v74, 16, v71
	v_and_b32_e32 v75, 0xffff0000, v71
	s_waitcnt lgkmcnt(3)
	v_pk_fma_f32 v[62:63], v[24:25], v[74:75], v[62:63]
	v_lshlrev_b32_e32 v76, 16, v77
	v_and_b32_e32 v77, 0xffff0000, v77
	s_waitcnt lgkmcnt(1)
	v_pk_fma_f32 v[36:37], v[36:37], v[76:77], v[62:63]
	v_lshlrev_b32_e32 v62, 16, v66
	v_and_b32_e32 v63, 0xffff0000, v66
	v_pk_fma_f32 v[62:63], v[14:15], v[62:63], v[6:7]
	v_lshlrev_b32_e32 v80, 16, v69
	v_and_b32_e32 v81, 0xffff0000, v69
	v_pk_fma_f32 v[62:63], v[26:27], v[80:81], v[62:63]
	v_lshlrev_b32_e32 v82, 16, v83
	v_and_b32_e32 v83, 0xffff0000, v83
	v_pk_fma_f32 v[38:39], v[38:39], v[82:83], v[62:63]
	v_lshlrev_b32_e32 v62, 16, v65
	v_and_b32_e32 v63, 0xffff0000, v65
	v_pk_fma_f32 v[62:63], v[16:17], v[62:63], v[8:9]
	v_lshlrev_b32_e32 v86, 16, v68
	v_and_b32_e32 v87, 0xffff0000, v68
	v_pk_fma_f32 v[62:63], v[28:29], v[86:87], v[62:63]
	v_lshlrev_b32_e32 v102, 16, v89
	v_and_b32_e32 v103, 0xffff0000, v89
	s_waitcnt lgkmcnt(0)
	v_pk_fma_f32 v[48:49], v[48:49], v[102:103], v[62:63]
	v_lshlrev_b32_e32 v62, 16, v64
	v_and_b32_e32 v63, 0xffff0000, v64
	v_pk_fma_f32 v[62:63], v[18:19], v[62:63], v[10:11]
	v_lshlrev_b32_e32 v108, 16, v67
	v_and_b32_e32 v109, 0xffff0000, v67
	s_and_b64 s[8:9], s[80:81], s[6:7]
	v_pk_fma_f32 v[62:63], v[30:31], v[108:109], v[62:63]
	v_lshlrev_b32_e32 v110, 16, v73
	v_and_b32_e32 v111, 0xffff0000, v73
	v_add_u32_e32 v57, 0x1f200, v57
	s_waitcnt vmcnt(4)
	v_cndmask_b32_e64 v105, v35, 0, s[8:9]
	v_cndmask_b32_e64 v107, v34, 0, s[8:9]
	v_cndmask_b32_e64 v85, v33, 0, s[8:9]
	v_cndmask_b32_e64 v79, v32, 0, s[8:9]
	ds_read_b128 v[32:35], v58 offset:768
	ds_read_b128 v[58:61], v58 offset:784
	v_pk_fma_f32 v[50:51], v[50:51], v[110:111], v[62:63]
	ds_read_b128 v[62:65], v57
	ds_read_b128 v[66:69], v57 offset:16
	v_cmp_gt_i32_e32 vcc, -1, v55
	s_and_b64 s[6:7], s[6:7], vcc
	v_pk_fma_f32 v[4:5], v[12:13], v[74:75], v[4:5]
	v_lshlrev_b32_e32 v78, 16, v79
	v_and_b32_e32 v79, 0xffff0000, v79
	s_waitcnt vmcnt(3)
	v_cndmask_b32_e64 v20, v20, 0, s[6:7]
	v_pk_fma_f32 v[4:5], v[24:25], v[76:77], v[4:5]
	v_pk_fma_f32 v[10:11], v[18:19], v[108:109], v[10:11]
	v_pk_fma_f32 v[8:9], v[16:17], v[86:87], v[8:9]
	v_pk_fma_f32 v[6:7], v[14:15], v[80:81], v[6:7]
	s_waitcnt lgkmcnt(1)
	v_pk_fma_f32 v[4:5], v[62:63], v[78:79], v[4:5]
	v_lshlrev_b32_e32 v12, 16, v20
	v_and_b32_e32 v13, 0xffff0000, v20
	v_lshlrev_b32_e32 v84, 16, v85
	v_and_b32_e32 v85, 0xffff0000, v85
	v_lshlrev_b32_e32 v106, 16, v107
	v_and_b32_e32 v107, 0xffff0000, v107
	v_lshlrev_b32_e32 v112, 16, v105
	v_and_b32_e32 v113, 0xffff0000, v105
	v_cndmask_b32_e64 v21, v21, 0, s[6:7]
	v_cndmask_b32_e64 v22, v22, 0, s[6:7]
	v_cndmask_b32_e64 v23, v23, 0, s[6:7]
	v_pk_fma_f32 v[10:11], v[30:31], v[110:111], v[10:11]
	v_pk_fma_f32 v[8:9], v[28:29], v[102:103], v[8:9]
	v_pk_fma_f32 v[6:7], v[26:27], v[82:83], v[6:7]
	v_pk_fma_f32 v[4:5], v[32:33], v[12:13], v[4:5]
	v_mul_lo_u32 v12, v55, s64
	v_pk_fma_f32 v[36:37], v[32:33], v[78:79], v[36:37]
	v_pk_fma_f32 v[38:39], v[34:35], v[84:85], v[38:39]
	s_waitcnt lgkmcnt(0)
	v_pk_fma_f32 v[10:11], v[68:69], v[112:113], v[10:11]
	v_lshlrev_b32_e32 v18, 16, v23
	v_and_b32_e32 v19, 0xffff0000, v23
	v_pk_fma_f32 v[8:9], v[66:67], v[106:107], v[8:9]
	v_lshlrev_b32_e32 v16, 16, v22
	v_and_b32_e32 v17, 0xffff0000, v22
	v_pk_fma_f32 v[6:7], v[64:65], v[84:85], v[6:7]
	v_lshlrev_b32_e32 v14, 16, v21
	v_and_b32_e32 v15, 0xffff0000, v21
	v_add3_u32 v1, s65, v12, v1
	v_pk_fma_f32 v[48:49], v[58:59], v[106:107], v[48:49]
	v_pk_fma_f32 v[50:51], v[60:61], v[112:113], v[50:51]
	v_pk_fma_f32 v[10:11], v[60:61], v[18:19], v[10:11]
	v_pk_fma_f32 v[8:9], v[58:59], v[16:17], v[8:9]
	v_pk_fma_f32 v[6:7], v[34:35], v[14:15], v[6:7]
	ds_write_b128 v1, v[36:39]
	ds_write_b128 v1, v[48:51] offset:16
	ds_write_b128 v1, v[4:7] offset:272
	ds_write_b128 v1, v[8:11] offset:288
	v_lshl_add_u64 v[4:5], s[0:1], 0, v[2:3]
	v_add_co_u32_e32 v4, vcc, s66, v4
	v_mov_b32_e32 v71, v3
	s_nop 0
	v_addc_co_u32_e32 v5, vcc, 0, v5, vcc
	v_lshl_add_u64 v[6:7], s[0:1], 0, v[70:71]
	v_add_co_u32_e32 v8, vcc, s66, v6
	v_mov_b32_e32 v1, v3
	s_nop 0
	v_addc_co_u32_e32 v9, vcc, 0, v7, vcc
	v_lshl_add_u64 v[0:1], s[0:1], 0, v[0:1]
	v_add_co_u32_e32 v0, vcc, s66, v0
	v_mov_b32_e32 v73, v3
	s_nop 0
	v_addc_co_u32_e32 v1, vcc, 0, v1, vcc
	v_lshl_add_u64 v[12:13], s[0:1], 0, v[72:73]
	v_add_co_u32_e32 v16, vcc, s66, v12
	global_load_dwordx4 v[4:7], v[4:5], off
	s_nop 0
	global_load_dwordx4 v[8:11], v[8:9], off
	v_addc_co_u32_e32 v17, vcc, 0, v13, vcc
	global_load_dwordx4 v[12:15], v[0:1], off
	s_nop 0
	global_load_dwordx4 v[16:19], v[16:17], off
	v_mul_lo_u32 v0, v90, s64
	v_add_u32_e32 v102, s65, v0
	s_waitcnt lgkmcnt(0)
	v_lshl_add_u32 v0, v88, 5, v102
	ds_read_b128 v[20:23], v0
	ds_read_b128 v[24:27], v0 offset:16
	v_mul_u32_u24_e32 v1, 0x48, v101
	v_lshlrev_b32_e32 v1, 1, v1
	v_readlane_b32 s0, v254, 49
	s_waitcnt lgkmcnt(1)
	v_cvt_pk_bf16_f32 v20, v20, v21
	v_cvt_pk_bf16_f32 v21, v22, v23
	v_add3_u32 v2, s0, v91, v1
	v_readlane_b32 s0, v254, 52
	s_waitcnt lgkmcnt(0)
	v_cvt_pk_bf16_f32 v22, v24, v25
	v_cvt_pk_bf16_f32 v23, v26, v27
	ds_read_b128 v[24:27], v2
	ds_read_b128 v[28:31], v2 offset:64
	v_add3_u32 v1, s0, v91, v1
	ds_read_b128 v[32:35], v1
	ds_read_b128 v[36:39], v1 offset:64
	ds_read_b128 v[48:51], v2 offset:2304
	ds_read_b128 v[58:61], v2 offset:2368
	ds_read_b128 v[62:65], v1 offset:2304
	ds_read_b128 v[66:69], v1 offset:2368
	ds_read_b128 v[70:73], v2 offset:4608
	ds_read_b128 v[74:77], v2 offset:4672
	ds_read_b128 v[78:81], v1 offset:4608
	ds_read_b128 v[82:85], v1 offset:4672
	ds_read_b128 v[106:109], v2 offset:6912
	ds_read_b128 v[110:113], v1 offset:6912
	ds_read_b128 v[114:117], v2 offset:6976
	ds_read_b128 v[118:121], v0 offset:128
	ds_read_b128 v[122:125], v0 offset:144
	ds_read_b128 v[126:129], v1 offset:6976
	s_waitcnt lgkmcnt(14)
	v_mfma_f32_16x16x32_bf16 v[24:27], v[20:23], v[24:27], 0
	v_lshlrev_b32_e32 v103, 2, v88
	v_or_b32_e32 v105, s34, v103
	v_or_b32_e32 v0, s40, v88
	v_mfma_f32_16x16x32_bf16 v[32:35], v[20:23], v[32:35], 0
	v_lshlrev_b32_e32 v89, 2, v101
	v_cmp_eq_u32_e32 vcc, 0, v0
	v_add_u32_e32 v2, s10, v89
	s_waitcnt lgkmcnt(13)
	v_mfma_f32_16x16x32_bf16 v[48:51], v[20:23], v[48:51], 0
	v_add_u32_e32 v0, s65, v89
	v_readlane_b32 s6, v255, 14
	v_readlane_b32 s7, v255, 15
	s_waitcnt lgkmcnt(11)
	v_mfma_f32_16x16x32_bf16 v[62:65], v[20:23], v[62:65], 0
	s_and_b64 s[6:7], s[6:7], vcc
	v_readlane_b32 s8, v255, 16
	v_cmp_eq_u32_e64 s[0:1], 0, v88
	s_waitcnt lgkmcnt(9)
	v_mfma_f32_16x16x32_bf16 v[70:73], v[20:23], v[70:73], 0
	s_waitcnt lgkmcnt(7)
	v_mfma_f32_16x16x32_bf16 v[78:81], v[20:23], v[78:81], 0
	s_waitcnt lgkmcnt(5)
	v_mfma_f32_16x16x32_bf16 v[106:109], v[20:23], v[106:109], 0
	s_waitcnt lgkmcnt(4)
	v_mfma_f32_16x16x32_bf16 v[20:23], v[20:23], v[110:113], 0
	s_waitcnt lgkmcnt(2)
	v_cvt_pk_bf16_f32 v110, v118, v119
	v_cvt_pk_bf16_f32 v111, v120, v121
	s_waitcnt lgkmcnt(1)
	v_cvt_pk_bf16_f32 v112, v122, v123
	v_cvt_pk_bf16_f32 v113, v124, v125
	s_nop 1
	v_mfma_f32_16x16x32_bf16 v[118:121], v[110:113], v[28:31], v[24:27]
	v_mfma_f32_16x16x32_bf16 v[122:125], v[110:113], v[36:39], v[32:35]
	v_mfma_f32_16x16x32_bf16 v[48:51], v[110:113], v[58:61], v[48:51]
	v_mul_lo_u32 v58, v105, s64
	v_add_u32_e32 v59, 0x110, v58
	v_add_u32_e32 v60, 0x220, v58
	v_add_u32_e32 v61, 0x330, v58
	v_mfma_f32_16x16x32_bf16 v[36:39], v[110:113], v[66:69], v[62:65]
	v_add_u32_e32 v57, v0, v59
	v_mfma_f32_16x16x32_bf16 v[32:35], v[110:113], v[74:77], v[70:73]
	v_add_u32_e32 v76, v0, v60
	v_add_u32_e32 v77, v0, v61
	v_mfma_f32_16x16x32_bf16 v[24:27], v[110:113], v[114:117], v[106:109]
	s_nop 2
	v_add_u32_e32 v106, v0, v58
	ds_read2st64_b32 v[0:1], v2 offset0:5 offset1:6
	ds_read_b32 v2, v2 offset:1792
	ds_read_b32 v62, v106
	ds_read_b32 v63, v57
	ds_read_b32 v64, v76
	ds_read_b32 v65, v77
	s_waitcnt lgkmcnt(5)
	v_fmamk_f32 v67, v122, 0xbfb8aa3b, v1
	v_fmamk_f32 v68, v119, 0xbfb8aa3b, v0
	v_exp_f32_e32 v67, v67
	v_exp_f32_e32 v69, v68
	v_fmamk_f32 v68, v123, 0xbfb8aa3b, v1
	v_exp_f32_e32 v70, v68
	v_fmamk_f32 v66, v118, 0xbfb8aa3b, v0
	v_add_f32_e32 v67, 1.0, v67
	v_exp_f32_e32 v66, v66
	v_rcp_f32_e32 v68, v67
	v_add_f32_e32 v67, 1.0, v69
	v_add_f32_e32 v69, 1.0, v70
	v_fmamk_f32 v70, v120, 0xbfb8aa3b, v0
	v_fmamk_f32 v0, v121, 0xbfb8aa3b, v0
	v_exp_f32_e32 v70, v70
	v_fmamk_f32 v71, v124, 0xbfb8aa3b, v1
	v_exp_f32_e32 v0, v0
	v_exp_f32_e32 v71, v71
	v_add_f32_e32 v66, 1.0, v66
	v_rcp_f32_e32 v66, v66
	v_rcp_f32_e32 v67, v67
	v_add_f32_e32 v70, 1.0, v70
	v_add_f32_e32 v0, 1.0, v0
	v_rcp_f32_e32 v70, v70
	v_add_f32_e32 v72, 1.0, v71
	v_rcp_f32_e32 v71, v0
	v_fmac_f32_e32 v1, 0xbfb8aa3b, v125
	s_waitcnt lgkmcnt(4)
	v_pk_mul_f32 v[66:67], v[2:3], v[66:67] op_sel_hi:[0,1]
	v_exp_f32_e32 v73, v1
	v_pk_mul_f32 v[0:1], v[2:3], v[70:71] op_sel_hi:[0,1]
	v_exp_f32_e32 v74, v66
	v_exp_f32_e32 v75, v67
	v_exp_f32_e32 v0, v0
	v_exp_f32_e32 v1, v1
	v_add_f32_e32 v2, 1.0, v73
	v_pk_mul_f32 v[70:71], v[74:75], v[74:75]
	v_rcp_f32_e32 v73, v2
	v_pk_mul_f32 v[66:67], v[0:1], v[0:1]
	v_sub_f32_e32 v2, 1.0, v70
	v_sqrt_f32_e32 v2, v2
	v_sub_f32_e32 v70, 1.0, v71
	v_sub_f32_e32 v66, 1.0, v66
	v_sub_f32_e32 v67, 1.0, v67
	v_rcp_f32_e32 v69, v69
	v_rcp_f32_e32 v72, v72
	v_sqrt_f32_e32 v71, v70
	v_sqrt_f32_e32 v66, v66
	v_sqrt_f32_e32 v67, v67
	v_cndmask_b32_e64 v70, v2, 1.0, s[6:7]
	v_pk_mul_f32 v[68:69], v[68:69], v[70:71]
	v_mfma_f32_16x16x32_bf16 v[28:31], v[110:113], v[82:85], v[78:81]
	v_mul_f32_e64 v66, v72, v66
	v_mul_f32_e64 v67, v73, v67
	s_waitcnt lgkmcnt(0)
	v_pk_mul_f32 v[64:65], v[64:65], v[66:67]
	v_pk_mul_f32 v[66:67], v[62:63], v[68:69]
	ds_write_b32 v57, v67
	v_fmac_f32_e32 v67, v75, v66
	v_mul_f32_e32 v2, v75, v74
	v_and_or_b32 v78, v95, 64, v101
	v_fma_f32 v57, v0, v67, v64
	v_mul_f32_e32 v2, v0, v2
	ds_write_b32 v77, v65
	v_fmac_f32_e32 v65, v1, v57
	v_mul_f32_e32 v57, v1, v2
	v_lshlrev_b32_e32 v2, 2, v78
	ds_bpermute_b32 v122, v2, v57
	ds_bpermute_b32 v136, v2, v65
	ds_bpermute_b32 v123, v2, v57 offset:64
	ds_bpermute_b32 v132, v2, v65 offset:64
	ds_bpermute_b32 v120, v2, v57 offset:128
	ds_bpermute_b32 v131, v2, v65 offset:128
	ds_bpermute_b32 v62, v2, v57 offset:192
	ds_bpermute_b32 v63, v2, v65 offset:192
	v_mfma_f32_16x16x32_bf16 v[20:23], v[110:113], v[126:129], v[20:23]
	s_waitcnt lgkmcnt(6)
	v_lshl_add_u32 v57, v101, 2, s8
	ds_write_b32 v106, v66
	ds_write_b32 v76, v64
	s_and_saveexec_b64 s[8:9], s[0:1]
	s_cbranch_execz .LBB0_211
	s_waitcnt lgkmcnt(7)
	v_mul_f32_e32 v64, v122, v123
	s_waitcnt lgkmcnt(6)
	v_fma_f32 v65, v136, v123, v132
	s_waitcnt lgkmcnt(5)
	v_mul_f32_e32 v64, v64, v120
	s_waitcnt lgkmcnt(4)
	v_fma_f32 v65, v65, v120, v131
	s_waitcnt lgkmcnt(3)
	v_mul_f32_e32 v64, v64, v62
	s_waitcnt lgkmcnt(2)
	v_fmac_f32_e32 v63, v65, v62
	ds_write2st64_b32 v57, v64, v63 offset1:8
.LBB0_211:
	s_or_b64 exec, exec, s[8:9]
	v_or_b32_e32 v118, 16, v101
	v_lshlrev_b32_e32 v65, 2, v118
	v_add_u32_e32 v64, s10, v65
	s_waitcnt lgkmcnt(2)
	ds_read2st64_b32 v[62:63], v64 offset0:5 offset1:6
	ds_read_b32 v64, v64 offset:1792
	v_add_u32_e32 v58, s65, v58
	v_add_u32_e32 v59, s65, v59
	v_add_u32_e32 v107, v58, v65
	s_waitcnt lgkmcnt(1)
	v_fmamk_f32 v37, v37, 0xbfb8aa3b, v63
	v_exp_f32_e32 v37, v37
	v_fmamk_f32 v38, v38, 0xbfb8aa3b, v63
	v_exp_f32_e32 v38, v38
	v_fmamk_f32 v48, v48, 0xbfb8aa3b, v62
	v_add_f32_e32 v37, 1.0, v37
	v_rcp_f32_e32 v69, v37
	v_fmamk_f32 v37, v50, 0xbfb8aa3b, v62
	v_exp_f32_e32 v37, v37
	v_fmamk_f32 v36, v36, 0xbfb8aa3b, v63
	v_fmamk_f32 v49, v49, 0xbfb8aa3b, v62
	v_exp_f32_e32 v66, v48
	v_add_f32_e32 v37, 1.0, v37
	v_exp_f32_e32 v67, v36
	v_exp_f32_e32 v49, v49
	v_rcp_f32_e32 v50, v37
	v_add_f32_e32 v37, 1.0, v38
	v_rcp_f32_e32 v70, v37
	v_fmamk_f32 v37, v51, 0xbfb8aa3b, v62
	v_exp_f32_e32 v37, v37
	v_add_f32_e32 v66, 1.0, v66
	v_add_f32_e32 v67, 1.0, v67
	v_add_f32_e32 v49, 1.0, v49
	v_fmac_f32_e32 v63, 0xbfb8aa3b, v39
	v_rcp_f32_e32 v66, v66
	v_rcp_f32_e32 v68, v67
	v_rcp_f32_e32 v67, v49
	v_exp_f32_e32 v38, v63
	v_add_f32_e32 v37, 1.0, v37
	v_rcp_f32_e32 v51, v37
	v_add_u32_e32 v49, s65, v60
	v_add_f32_e32 v37, 1.0, v38
	v_add_u32_e32 v38, s65, v61
	s_waitcnt lgkmcnt(0)
	v_pk_mul_f32 v[60:61], v[64:65], v[66:67] op_sel_hi:[0,1]
	v_exp_f32_e32 v78, v60
	v_exp_f32_e32 v79, v61
	v_pk_mul_f32 v[50:51], v[64:65], v[50:51] op_sel_hi:[0,1]
	v_exp_f32_e32 v76, v50
	v_exp_f32_e32 v77, v51
	v_add_u32_e32 v108, v59, v65
	v_add_u32_e32 v111, v49, v65
	v_add_u32_e32 v112, v38, v65
	v_pk_mul_f32 v[64:65], v[78:79], v[78:79]
	v_rcp_f32_e32 v71, v37
	v_sub_f32_e32 v37, 1.0, v64
	v_pk_mul_f32 v[62:63], v[76:77], v[76:77]
	v_sqrt_f32_e32 v39, v37
	v_sub_f32_e32 v37, 1.0, v65
	v_sqrt_f32_e32 v65, v37
	v_sub_f32_e32 v37, 1.0, v62
	v_sqrt_f32_e32 v62, v37
	v_sub_f32_e32 v37, 1.0, v63
	ds_read_b32 v50, v107
	ds_read_b32 v51, v108
	ds_read_b32 v60, v111
	ds_read_b32 v61, v112
	v_sqrt_f32_e32 v63, v37
	v_cndmask_b32_e64 v64, v39, 1.0, s[6:7]
	v_pk_mul_f32 v[64:65], v[68:69], v[64:65]
	v_or_b32_e32 v36, 64, v2
	v_pk_mul_f32 v[62:63], v[70:71], v[62:63]
	v_or_b32_e32 v48, 0x80, v2
	s_waitcnt lgkmcnt(0)
	v_pk_mul_f32 v[60:61], v[60:61], v[62:63]
	v_pk_mul_f32 v[62:63], v[50:51], v[64:65]
	ds_write_b32 v108, v63
	v_fmac_f32_e32 v63, v79, v62
	v_mul_f32_e32 v39, v79, v78
	v_fma_f32 v50, v76, v63, v60
	v_mul_f32_e32 v39, v76, v39
	ds_write_b32 v112, v61
	v_fmac_f32_e32 v61, v77, v50
	v_mul_f32_e32 v39, v77, v39
	v_or_b32_e32 v37, 0xc0, v2
	ds_bpermute_b32 v126, v2, v39
	ds_bpermute_b32 v130, v2, v61
	ds_bpermute_b32 v128, v36, v39
	ds_bpermute_b32 v129, v36, v61
	ds_bpermute_b32 v124, v48, v39
	ds_bpermute_b32 v125, v48, v61
	ds_bpermute_b32 v50, v37, v39
	ds_bpermute_b32 v39, v37, v61
	s_waitcnt lgkmcnt(6)
	ds_write_b32 v107, v62
	ds_write_b32 v111, v60
	s_and_saveexec_b64 s[8:9], s[0:1]
	s_cbranch_execz .LBB0_213
	s_waitcnt lgkmcnt(7)
	v_mul_f32_e32 v51, v126, v128
	s_waitcnt lgkmcnt(6)
	v_fma_f32 v60, v130, v128, v129
	s_waitcnt lgkmcnt(5)
	v_mul_f32_e32 v51, v51, v124
	s_waitcnt lgkmcnt(4)
	v_fma_f32 v60, v60, v124, v125
	s_waitcnt lgkmcnt(3)
	v_mul_f32_e32 v51, v51, v50
	s_waitcnt lgkmcnt(2)
	v_fmac_f32_e32 v39, v60, v50
	v_add_u32_e32 v50, 64, v57
	ds_write2st64_b32 v50, v51, v39 offset1:8
.LBB0_213:
	s_or_b64 exec, exec, s[8:9]
	v_or_b32_e32 v121, 32, v101
	s_waitcnt lgkmcnt(2)
	v_lshlrev_b32_e32 v39, 2, v121
	v_add_u32_e32 v60, s10, v39
	ds_read2st64_b32 v[50:51], v60 offset0:5 offset1:6
	ds_read_b32 v60, v60 offset:1792
	v_add_u32_e32 v109, v58, v39
	v_add_u32_e32 v110, v59, v39
	v_add_u32_e32 v115, v49, v39
	s_waitcnt lgkmcnt(1)
	v_fmamk_f32 v32, v32, 0xbfb8aa3b, v50
	v_fmamk_f32 v28, v28, 0xbfb8aa3b, v51
	v_exp_f32_e32 v32, v32
	v_exp_f32_e32 v28, v28
	v_fmamk_f32 v33, v33, 0xbfb8aa3b, v50
	v_fmamk_f32 v29, v29, 0xbfb8aa3b, v51
	v_add_f32_e32 v32, 1.0, v32
	v_add_f32_e32 v61, 1.0, v28
	v_exp_f32_e32 v33, v33
	v_rcp_f32_e32 v28, v32
	v_rcp_f32_e32 v32, v61
	v_exp_f32_e32 v61, v29
	v_fmamk_f32 v30, v30, 0xbfb8aa3b, v51
	v_add_f32_e32 v29, 1.0, v33
	v_fmamk_f32 v34, v34, 0xbfb8aa3b, v50
	v_add_f32_e32 v33, 1.0, v61
	v_exp_f32_e32 v61, v30
	v_fmamk_f32 v30, v35, 0xbfb8aa3b, v50
	v_exp_f32_e32 v34, v34
	v_exp_f32_e32 v35, v30
	v_rcp_f32_e32 v29, v29
	v_fmac_f32_e32 v51, 0xbfb8aa3b, v31
	v_add_f32_e32 v30, 1.0, v34
	v_add_f32_e32 v35, 1.0, v35
	v_rcp_f32_e32 v30, v30
	v_rcp_f32_e32 v31, v35
	s_waitcnt lgkmcnt(0)
	v_pk_mul_f32 v[28:29], v[60:61], v[28:29] op_sel_hi:[0,1]
	v_exp_f32_e32 v82, v28
	v_exp_f32_e32 v83, v29
	v_pk_mul_f32 v[30:31], v[60:61], v[30:31] op_sel_hi:[0,1]
	v_exp_f32_e32 v80, v30
	v_exp_f32_e32 v81, v31
	v_exp_f32_e32 v50, v51
	v_pk_mul_f32 v[30:31], v[82:83], v[82:83]
	v_rcp_f32_e32 v33, v33
	v_sub_f32_e32 v30, 1.0, v30
	v_pk_mul_f32 v[28:29], v[80:81], v[80:81]
	v_sqrt_f32_e32 v30, v30
	v_sub_f32_e32 v31, 1.0, v31
	v_add_f32_e32 v34, 1.0, v61
	v_add_f32_e32 v35, 1.0, v50
	v_add_u32_e32 v116, v38, v39
	v_sqrt_f32_e32 v31, v31
	v_sub_f32_e32 v28, 1.0, v28
	v_sub_f32_e32 v29, 1.0, v29
	ds_read_b32 v50, v109
	ds_read_b32 v60, v115
	ds_read_b32 v61, v116
	ds_read_b32 v51, v110
	v_rcp_f32_e32 v34, v34
	v_rcp_f32_e32 v35, v35
	v_sqrt_f32_e32 v28, v28
	v_sqrt_f32_e32 v29, v29
	v_cndmask_b32_e64 v30, v30, 1.0, s[6:7]
	v_pk_mul_f32 v[30:31], v[32:33], v[30:31]
	v_pk_mul_f32 v[28:29], v[34:35], v[28:29]
	s_waitcnt lgkmcnt(0)
	v_pk_mul_f32 v[30:31], v[50:51], v[30:31]
	v_pk_mul_f32 v[32:33], v[60:61], v[28:29]
	ds_write_b32 v110, v31
	v_fmac_f32_e32 v31, v83, v30
	v_mul_f32_e32 v28, v83, v82
	v_fma_f32 v29, v80, v31, v32
	v_mul_f32_e32 v28, v80, v28
	ds_write_b32 v116, v33
	v_fmac_f32_e32 v33, v81, v29
	v_mul_f32_e32 v28, v81, v28
	ds_bpermute_b32 v135, v2, v28
	ds_bpermute_b32 v139, v2, v33
	ds_bpermute_b32 v137, v36, v28
	ds_bpermute_b32 v138, v36, v33
	ds_bpermute_b32 v133, v48, v28
	ds_bpermute_b32 v134, v48, v33
	ds_bpermute_b32 v29, v37, v28
	ds_bpermute_b32 v28, v37, v33
	s_waitcnt lgkmcnt(6)
	ds_write_b32 v109, v30
	ds_write_b32 v115, v32
	s_and_saveexec_b64 s[8:9], s[0:1]
	s_cbranch_execz .LBB0_215
	s_waitcnt lgkmcnt(7)
	v_mul_f32_e32 v30, v135, v137
	s_waitcnt lgkmcnt(6)
	v_fma_f32 v31, v139, v137, v138
	s_waitcnt lgkmcnt(5)
	v_mul_f32_e32 v30, v30, v133
	s_waitcnt lgkmcnt(4)
	v_fma_f32 v31, v31, v133, v134
	s_waitcnt lgkmcnt(3)
	v_mul_f32_e32 v30, v30, v29
	s_waitcnt lgkmcnt(2)
	v_fmac_f32_e32 v28, v31, v29
	v_add_u32_e32 v29, 0x80, v57
	ds_write2st64_b32 v29, v30, v28 offset1:8
.LBB0_215:
	s_or_b64 exec, exec, s[8:9]
	v_or_b32_e32 v127, 48, v101
	v_lshlrev_b32_e32 v31, 2, v127
	v_add_u32_e32 v30, s10, v31
	s_waitcnt lgkmcnt(2)
	ds_read2st64_b32 v[28:29], v30 offset0:5 offset1:6
	ds_read_b32 v30, v30 offset:1792
	v_add_u32_e32 v113, v58, v31
	v_add_u32_e32 v114, v59, v31
	v_add_u32_e32 v117, v49, v31
	s_waitcnt lgkmcnt(1)
	v_fmamk_f32 v24, v24, 0xbfb8aa3b, v28
	v_fmamk_f32 v20, v20, 0xbfb8aa3b, v29
	v_exp_f32_e32 v24, v24
	v_exp_f32_e32 v20, v20
	v_fmamk_f32 v25, v25, 0xbfb8aa3b, v28
	v_fmamk_f32 v21, v21, 0xbfb8aa3b, v29
	v_add_f32_e32 v24, 1.0, v24
	v_add_f32_e32 v32, 1.0, v20
	v_exp_f32_e32 v25, v25
	v_rcp_f32_e32 v20, v24
	v_rcp_f32_e32 v24, v32
	v_exp_f32_e32 v32, v21
	v_fmamk_f32 v22, v22, 0xbfb8aa3b, v29
	v_add_f32_e32 v21, 1.0, v25
	v_fmamk_f32 v26, v26, 0xbfb8aa3b, v28
	v_add_f32_e32 v25, 1.0, v32
	v_exp_f32_e32 v32, v22
	v_fmamk_f32 v22, v27, 0xbfb8aa3b, v28
	v_exp_f32_e32 v26, v26
	v_exp_f32_e32 v27, v22
	v_rcp_f32_e32 v21, v21
	v_fmac_f32_e32 v29, 0xbfb8aa3b, v23
	v_add_f32_e32 v22, 1.0, v26
	v_add_f32_e32 v27, 1.0, v27
	v_rcp_f32_e32 v22, v22
	v_rcp_f32_e32 v23, v27
	s_waitcnt lgkmcnt(0)
	v_pk_mul_f32 v[20:21], v[30:31], v[20:21] op_sel_hi:[0,1]
	v_exp_f32_e32 v86, v20
	v_exp_f32_e32 v87, v21
	v_pk_mul_f32 v[22:23], v[30:31], v[22:23] op_sel_hi:[0,1]
	v_exp_f32_e32 v84, v22
	v_exp_f32_e32 v85, v23
	v_exp_f32_e32 v28, v29
	v_pk_mul_f32 v[22:23], v[86:87], v[86:87]
	v_rcp_f32_e32 v25, v25
	v_sub_f32_e32 v22, 1.0, v22
	v_pk_mul_f32 v[20:21], v[84:85], v[84:85]
	v_sqrt_f32_e32 v22, v22
	v_sub_f32_e32 v23, 1.0, v23
	v_add_f32_e32 v26, 1.0, v32
	v_add_f32_e32 v27, 1.0, v28
	v_add_u32_e32 v119, v38, v31
	v_sqrt_f32_e32 v23, v23
	v_sub_f32_e32 v20, 1.0, v20
	v_sub_f32_e32 v21, 1.0, v21
	ds_read_b32 v28, v113
	ds_read_b32 v30, v117
	ds_read_b32 v31, v119
	ds_read_b32 v29, v114
	v_rcp_f32_e32 v26, v26
	v_rcp_f32_e32 v27, v27
	v_sqrt_f32_e32 v20, v20
	v_sqrt_f32_e32 v21, v21
	v_cndmask_b32_e64 v22, v22, 1.0, s[6:7]
	v_pk_mul_f32 v[22:23], v[24:25], v[22:23]
	v_pk_mul_f32 v[20:21], v[26:27], v[20:21]
	s_waitcnt lgkmcnt(0)
	v_pk_mul_f32 v[22:23], v[28:29], v[22:23]
	v_pk_mul_f32 v[24:25], v[30:31], v[20:21]
	ds_write_b32 v114, v23
	v_fmac_f32_e32 v23, v87, v22
	v_mul_f32_e32 v20, v87, v86
	v_fma_f32 v21, v84, v23, v24
	v_mul_f32_e32 v20, v84, v20
	ds_write_b32 v119, v25
	v_fmac_f32_e32 v25, v85, v21
	v_mul_f32_e32 v20, v85, v20
	ds_bpermute_b32 v142, v2, v20
	ds_bpermute_b32 v146, v2, v25
	ds_bpermute_b32 v143, v36, v20
	ds_bpermute_b32 v145, v36, v25
	ds_bpermute_b32 v140, v48, v20
	ds_bpermute_b32 v141, v48, v25
	ds_bpermute_b32 v20, v37, v20
	ds_bpermute_b32 v2, v37, v25
	s_waitcnt lgkmcnt(6)
	ds_write_b32 v113, v22
	ds_write_b32 v117, v24
	s_and_saveexec_b64 s[6:7], s[0:1]
	s_cbranch_execz .LBB0_217
	s_waitcnt lgkmcnt(7)
	v_mul_f32_e32 v21, v142, v143
	s_waitcnt lgkmcnt(6)
	v_fma_f32 v22, v146, v143, v145
	s_waitcnt lgkmcnt(5)
	v_mul_f32_e32 v21, v21, v140
	s_waitcnt lgkmcnt(4)
	v_fma_f32 v22, v22, v140, v141
	s_waitcnt lgkmcnt(3)
	v_mul_f32_e32 v21, v21, v20
	s_waitcnt lgkmcnt(2)
	v_fmac_f32_e32 v2, v22, v20
	v_add_u32_e32 v20, 0xc0, v57
	ds_write2st64_b32 v20, v21, v2 offset1:8
